# final LayerNorm: next row prefetched into a second register set while the current row is reduced
# speedup vs baseline: 1.0023x; 1.0023x over previous
; #define GASP __attribute__((address_space(1)))
; __device__ __forceinline__ void phase_ln(const bf16_t* src, float* dstf, bf16_t* dstb, const float* gam, const float* bet) {
;     const int lane = threadIdx.x & 63, gw = blockIdx.x * 8 + (threadIdx.x >> 6), NGW = gridDim.x * 8;
;     f32x4 gg[4], bb[4];
; #pragma unroll
;     for (int j = 0; j < 4; ++j) { gg[j] = ((const GASP f32x4*)gam)[64 * j + lane]; bb[j] = ((const GASP f32x4*)bet)[64 * j + lane]; }
;     for (int row = gw; row < M; row += NGW) {
;         const GASP u32x2* xr = (const GASP u32x2*)(src + (size_t)row * D) + lane;
;         u32x2 raw[4];
; #pragma unroll
;         for (int j = 0; j < 4; ++j) raw[j] = xr[64 * j];
.LBB0_1767:
	s_cmp_lt_i32 s54, 15
	s_cselect_b64 s[0:1], -1, 0
	s_cmp_gt_i32 s55, 14
	s_cselect_b64 s[4:5], -1, 0
	s_and_b64 s[0:1], s[0:1], s[4:5]
	s_andn2_b64 vcc, exec, s[0:1]
	s_cbranch_vccnz .LBB0_1771
	s_waitcnt vmcnt(0)
	v_lshl_add_u32 v32, s2, 3, v209
	s_mov_b32 s0, 0x8400
	v_cmp_gt_i32_e32 vcc, s0, v32
	s_and_saveexec_b64 s[0:1], vcc
	s_cbranch_execz .LBB0_1771
	v_readlane_b32 s4, v252, 1
	v_readlane_b32 s5, v252, 2
	s_load_dwordx4 s[0:3], s[4:5], 0x100
	s_load_dwordx2 s[6:7], s[4:5], 0x110
	v_and_b32_e32 v34, 63, v208
	v_lshlrev_b32_e32 v46, 4, v34
	v_mbcnt_lo_u32_b32 v33, -1, 0
	s_waitcnt lgkmcnt(0)
	global_load_dwordx4 v[0:3], v46, s[0:1]
	global_load_dwordx4 v[4:7], v46, s[2:3]
	global_load_dwordx4 v[8:11], v46, s[0:1] offset:1024
	global_load_dwordx4 v[12:15], v46, s[2:3] offset:1024
	global_load_dwordx4 v[16:19], v46, s[0:1] offset:2048
	global_load_dwordx4 v[20:23], v46, s[2:3] offset:2048
	global_load_dwordx4 v[24:27], v46, s[0:1] offset:3072
	global_load_dwordx4 v[28:31], v46, s[2:3] offset:3072
	v_mbcnt_hi_u32_b32 v33, -1, v33
	v_and_b32_e32 v36, 64, v33
	v_add_u32_e32 v36, 64, v36
	v_xor_b32_e32 v37, 1, v33
	v_cmp_lt_i32_e32 vcc, v37, v36
	s_lshl_b32 s2, s82, 3
	s_mov_b64 s[0:1], 0x3021000
	v_cndmask_b32_e32 v37, v33, v37, vcc
	v_lshlrev_b32_e32 v40, 2, v37
	v_xor_b32_e32 v37, 2, v33
	v_cmp_lt_i32_e32 vcc, v37, v36
	s_ashr_i32 s3, s2, 31
	v_mov_b32_e32 v35, 0
	v_cndmask_b32_e32 v37, v33, v37, vcc
	v_lshlrev_b32_e32 v41, 2, v37
	v_xor_b32_e32 v37, 4, v33
	v_cmp_lt_i32_e32 vcc, v37, v36
	s_lshl_b64 s[4:5], s[2:3], 11
	s_mov_b64 s[8:9], 0
	v_cndmask_b32_e32 v37, v33, v37, vcc
	v_lshlrev_b32_e32 v42, 2, v37
	v_xor_b32_e32 v37, 8, v33
	v_cmp_lt_i32_e32 vcc, v37, v36
	v_lshlrev_b32_e32 v34, 3, v34
	s_mov_b32 s10, 0x83ff
	v_cndmask_b32_e32 v37, v33, v37, vcc
	v_lshlrev_b32_e32 v43, 2, v37
	v_xor_b32_e32 v37, 16, v33
	v_cmp_lt_i32_e32 vcc, v37, v36
	s_nop 1
	v_cndmask_b32_e32 v37, v33, v37, vcc
	v_lshlrev_b32_e32 v44, 2, v37
	v_xor_b32_e32 v37, 32, v33
	v_cmp_lt_i32_e32 vcc, v37, v36
	s_nop 1
	v_cndmask_b32_e32 v33, v33, v37, vcc
	v_lshlrev_b32_e32 v45, 2, v33
	v_ashrrev_i32_e32 v33, 31, v32
	v_lshlrev_b64 v[36:37], 11, v[32:33]
	v_lshlrev_b64 v[38:39], 12, v[32:33]
	v_lshl_add_u64 v[36:37], s[52:53], 0, v[36:37]
	v_or_b32_e32 v38, v38, v46
	v_lshl_add_u64 v[36:37], v[36:37], 0, s[0:1]
	v_lshl_add_u64 v[38:39], s[6:7], 0, v[38:39]
	s_mov_b64 s[0:1], 0xc00
	v_lshl_add_u64 v[38:39], v[38:39], 0, s[0:1]
	s_lshl_b64 s[6:7], s[2:3], 12
	v_mov_b32_e32 v33, 0x3727c5ac
	s_mov_b32 s3, 0xf800000
	v_mov_b32_e32 v46, 0x260
	v_lshl_add_u64 v[48:49], v[36:37], 0, v[34:35]
	global_load_dwordx2 v[50:51], v[48:49], off
	global_load_dwordx2 v[52:53], v[48:49], off offset:512
	global_load_dwordx2 v[54:55], v[48:49], off offset:1024
	global_load_dwordx2 v[56:57], v[48:49], off offset:1536
; #define GASP __attribute__((address_space(1)))
; __device__ __forceinline__ void phase_ln(const bf16_t* src, float* dstf, bf16_t* dstb, const float* gam, const float* bet) {
;     ...
;     for (int row = gw; row < M; row += NGW) {
;         const GASP u32x2* xr = (const GASP u32x2*)(src + (size_t)row * D) + lane;
;         u32x2 raw[4];
; #pragma unroll
;         for (int j = 0; j < 4; ++j) raw[j] = xr[64 * j];
;         f32x4 v[4]; float s = 0.f;
; #pragma unroll
;         for (int j = 0; j < 4; ++j) { v[j] = (f32x4){__uint_as_float(raw[j].x << 16), __uint_as_float(raw[j].x & 0xffff0000u), __uint_as_float(raw[j].y << 16), __uint_as_float(raw[j].y & 0xffff0000u)};
;             s += (v[j][0] + v[j][1]) + (v[j][2] + v[j][3]); }
;         const float mean = wave_sum(s) * (1.f / D); float s2 = 0.f;
; #pragma unroll
;         for (int j = 0; j < 4; ++j) { v[j] = v[j] - mean; s2 += (v[j][0] * v[j][0] + v[j][1] * v[j][1]) + (v[j][2] * v[j][2] + v[j][3] * v[j][3]); }
;         const float rstd = 1.f / sqrtf(wave_sum(s2) * (1.f / D) + LN_EPS);
; #pragma unroll
;         for (int j = 0; j < 4; ++j) {
;             const f32x4 y = v[j] * rstd * gg[j] + bb[j];
;             __builtin_nontemporal_store(y, (GASP f32x4*)(dstf + (size_t)row * D) + 64 * j + lane);
;             if (dstb) { u32x2 w; w.x = pk2(y[0], y[1]); w.y = pk2(y[2], y[3]); ((GASP u32x2*)(dstb + (size_t)row * D))[64 * j + lane] = w; }
;         }
;     }
.LBB0_1770:
	v_lshl_add_u64 v[36:37], v[36:37], 0, s[4:5]
	v_lshl_add_u64 v[48:49], v[36:37], 0, v[34:35]
	global_load_dwordx2 v[82:83], v[48:49], off
	global_load_dwordx2 v[84:85], v[48:49], off offset:512
	global_load_dwordx2 v[86:87], v[48:49], off offset:1024
	global_load_dwordx2 v[88:89], v[48:49], off offset:1536
	v_add_u32_e32 v32, s2, v32
	v_cmp_lt_i32_e32 vcc, s10, v32
	s_or_b64 s[8:9], vcc, s[8:9]
	s_waitcnt vmcnt(4)
	v_lshlrev_b32_e32 v49, 16, v51
	v_lshlrev_b32_e32 v48, 16, v50
	v_and_b32_e32 v51, 0xffff0000, v51
	v_and_b32_e32 v50, 0xffff0000, v50
	v_lshlrev_b32_e32 v59, 16, v53
	v_lshlrev_b32_e32 v58, 16, v52
	v_and_b32_e32 v53, 0xffff0000, v53
	v_and_b32_e32 v52, 0xffff0000, v52
	v_pk_add_f32 v[68:69], v[48:49], v[50:51]
	v_pk_add_f32 v[70:71], v[58:59], v[52:53]
	v_lshlrev_b32_e32 v60, 16, v54
	v_and_b32_e32 v61, 0xffff0000, v54
	v_lshlrev_b32_e32 v54, 16, v55
	v_and_b32_e32 v55, 0xffff0000, v55
	v_and_b32_e32 v65, 0xffff0000, v56
	v_add_f32_e32 v47, v68, v69
	v_pk_add_f32 v[68:69], v[70:71], v[70:71] op_sel:[0,1] op_sel_hi:[1,0]
	v_lshlrev_b32_e32 v63, 16, v56
	v_lshlrev_b32_e32 v67, 16, v57
	v_and_b32_e32 v57, 0xffff0000, v57
	v_add_f32_e32 v66, v60, v61
	v_add_f32_e32 v56, v54, v55
	v_add_f32_e32 v62, 0, v47
	v_mov_b32_e32 v69, v65
	v_pk_add_f32 v[70:71], v[66:67], v[56:57]
	v_pk_add_f32 v[68:69], v[62:63], v[68:69]
	s_nop 0
	v_pk_add_f32 v[68:69], v[68:69], v[70:71]
	s_nop 0
	v_add_f32_e32 v47, v68, v69
	ds_bpermute_b32 v56, v40, v47
	s_waitcnt lgkmcnt(0)
	v_add_f32_e32 v47, v47, v56
	ds_bpermute_b32 v56, v41, v47
	s_waitcnt lgkmcnt(0)
	v_add_f32_e32 v47, v47, v56
	ds_bpermute_b32 v56, v42, v47
	s_waitcnt lgkmcnt(0)
	v_add_f32_e32 v47, v47, v56
	ds_bpermute_b32 v56, v43, v47
	s_waitcnt lgkmcnt(0)
	v_add_f32_e32 v47, v47, v56
	ds_bpermute_b32 v56, v44, v47
	s_waitcnt lgkmcnt(0)
	v_add_f32_e32 v47, v47, v56
	ds_bpermute_b32 v56, v45, v47
	s_waitcnt lgkmcnt(0)
	v_add_f32_e32 v47, v47, v56
	v_fmac_f32_e32 v50, 0xba800000, v47
	v_fmac_f32_e32 v51, 0xba800000, v47
	v_fmac_f32_e32 v49, 0xba800000, v47
	v_fmac_f32_e32 v52, 0xba800000, v47
	v_fmac_f32_e32 v53, 0xba800000, v47
	v_fmac_f32_e32 v59, 0xba800000, v47
	v_fmac_f32_e32 v48, 0xba800000, v47
	v_fmac_f32_e32 v58, 0xba800000, v47
	v_fmac_f32_e32 v60, 0xba800000, v47
	v_mov_b32_e32 v68, v49
	v_mov_b32_e32 v69, v51
	v_mov_b32_e32 v49, v50
	v_mov_b32_e32 v50, v59
	v_mov_b32_e32 v51, v53
	v_mov_b32_e32 v59, v52
	v_fmac_f32_e32 v61, 0xba800000, v47
	v_fmac_f32_e32 v54, 0xba800000, v47
	v_mul_f32_e32 v52, v60, v60
	v_pk_mul_f32 v[70:71], v[68:69], v[68:69]
	v_pk_mul_f32 v[72:73], v[48:49], v[48:49]
	v_pk_mul_f32 v[74:75], v[50:51], v[50:51]
	v_pk_mul_f32 v[76:77], v[58:59], v[58:59]
	v_fmac_f32_e32 v55, 0xba800000, v47
	v_fmac_f32_e32 v63, 0xba800000, v47
	v_mul_f32_e32 v62, v54, v54
	v_pk_fma_f32 v[52:53], v[60:61], v[60:61], v[52:53] op_sel_hi:[1,1,0]
	v_pk_mov_b32 v[80:81], v[72:73], v[70:71] op_sel:[1,0]
	v_mov_b32_e32 v73, v71
	v_pk_mov_b32 v[70:71], v[76:77], v[74:75] op_sel:[1,0]
	v_mov_b32_e32 v77, v75
	v_mov_b32_e32 v64, v63
	v_pk_fma_f32 v[78:79], v[54:55], v[54:55], v[62:63] op_sel_hi:[1,1,0]
	v_mul_f32_e32 v52, v63, v63
	v_pk_add_f32 v[62:63], v[80:81], v[72:73]
	v_pk_add_f32 v[70:71], v[70:71], v[76:77]
	v_fmac_f32_e32 v57, 0xba800000, v47
	v_fmac_f32_e32 v67, 0xba800000, v47
	v_fmac_f32_e32 v65, 0xba800000, v47
	v_pk_add_f32 v[62:63], v[62:63], v[62:63] op_sel_hi:[0,1]
	v_pk_add_f32 v[70:71], v[70:71], v[70:71] op_sel_hi:[0,1]
	v_mul_f32_e32 v78, v65, v65
	v_mul_f32_e32 v62, v67, v67
	v_mul_f32_e32 v70, v57, v57
	v_pk_add_f32 v[52:53], v[52:53], v[78:79]
	v_pk_add_f32 v[62:63], v[62:63], v[70:71]
	v_mov_b32_e32 v56, v67
	v_pk_add_f32 v[52:53], v[52:53], v[62:63]
	s_nop 0
	v_add_f32_e32 v47, v52, v53
	ds_bpermute_b32 v52, v40, v47
	s_waitcnt lgkmcnt(0)
	v_add_f32_e32 v47, v47, v52
	ds_bpermute_b32 v52, v41, v47
	s_waitcnt lgkmcnt(0)
	v_add_f32_e32 v47, v47, v52
	ds_bpermute_b32 v52, v42, v47
	s_waitcnt lgkmcnt(0)
	v_add_f32_e32 v47, v47, v52
	ds_bpermute_b32 v52, v43, v47
	s_waitcnt lgkmcnt(0)
	v_add_f32_e32 v47, v47, v52
	ds_bpermute_b32 v52, v44, v47
	s_waitcnt lgkmcnt(0)
	v_add_f32_e32 v47, v47, v52
	ds_bpermute_b32 v52, v45, v47
	s_waitcnt lgkmcnt(0)
	v_add_f32_e32 v47, v47, v52
	v_fmamk_f32 v47, v47, 0x3a800000, v33
	v_mul_f32_e32 v52, 0x4f800000, v47
	v_cmp_gt_f32_e32 vcc, s3, v47
	s_nop 1
	v_cndmask_b32_e32 v47, v47, v52, vcc
	v_sqrt_f32_e32 v52, v47
	s_nop 0
	v_add_u32_e32 v53, -1, v52
	v_add_u32_e32 v62, 1, v52
	v_fma_f32 v63, -v53, v52, v47
	v_fma_f32 v66, -v62, v52, v47
	v_cmp_ge_f32_e64 s[0:1], 0, v63
	s_nop 1
	v_cndmask_b32_e64 v52, v52, v53, s[0:1]
	v_cmp_lt_f32_e64 s[0:1], 0, v66
	s_nop 1
	v_cndmask_b32_e64 v52, v52, v62, s[0:1]
	v_mul_f32_e32 v53, 0x37800000, v52
	v_cndmask_b32_e32 v52, v52, v53, vcc
	v_cmp_class_f32_e32 vcc, v47, v46
	s_nop 1
	v_cndmask_b32_e32 v47, v52, v47, vcc
	v_div_scale_f32 v52, s[0:1], v47, v47, 1.0
	v_rcp_f32_e32 v62, v52
	v_div_scale_f32 v53, vcc, 1.0, v47, 1.0
	v_fma_f32 v63, -v52, v62, 1.0
	v_fmac_f32_e32 v62, v63, v62
	v_mul_f32_e32 v63, v53, v62
	v_fma_f32 v66, -v52, v63, v53
	v_fmac_f32_e32 v63, v66, v62
	v_fma_f32 v52, -v52, v63, v53
	v_div_fmas_f32 v52, v52, v62, v63
	v_div_fixup_f32 v52, v52, v47, 1.0
	v_pk_mul_f32 v[48:49], v[48:49], v[52:53] op_sel_hi:[1,0]
	v_pk_mul_f32 v[62:63], v[68:69], v[52:53] op_sel_hi:[1,0]
	v_pk_mul_f32 v[58:59], v[58:59], v[52:53] op_sel_hi:[1,0]
	v_pk_mul_f32 v[66:67], v[50:51], v[52:53] op_sel_hi:[1,0]
	v_pk_mul_f32 v[60:61], v[60:61], v[52:53] op_sel_hi:[1,0]
	v_pk_mul_f32 v[68:69], v[54:55], v[52:53] op_sel_hi:[1,0]
	v_pk_mul_f32 v[64:65], v[64:65], v[52:53] op_sel_hi:[1,0]
	v_pk_mul_f32 v[70:71], v[56:57], v[52:53] op_sel_hi:[1,0]
	v_pk_fma_f32 v[50:51], v[2:3], v[62:63], v[6:7]
	v_pk_fma_f32 v[48:49], v[0:1], v[48:49], v[4:5]
	v_pk_fma_f32 v[54:55], v[10:11], v[66:67], v[14:15]
	v_pk_fma_f32 v[52:53], v[8:9], v[58:59], v[12:13]
	v_pk_fma_f32 v[58:59], v[18:19], v[68:69], v[22:23]
	v_pk_fma_f32 v[56:57], v[16:17], v[60:61], v[20:21]
	v_pk_fma_f32 v[62:63], v[26:27], v[70:71], v[30:31]
	v_pk_fma_f32 v[60:61], v[24:25], v[64:65], v[28:29]
	global_store_dwordx4 v[38:39], v[48:51], off offset:-3072 nt
	global_store_dwordx4 v[38:39], v[52:55], off offset:-2048 nt
	global_store_dwordx4 v[38:39], v[56:59], off offset:-1024 nt
	global_store_dwordx4 v[38:39], v[60:63], off nt
	v_lshl_add_u64 v[38:39], v[38:39], 0, s[6:7]
	s_waitcnt vmcnt(4)
	v_mov_b32_e32 v50, v82
	v_mov_b32_e32 v51, v83
	v_mov_b32_e32 v52, v84
	v_mov_b32_e32 v53, v85
	v_mov_b32_e32 v54, v86
	v_mov_b32_e32 v55, v87
	v_mov_b32_e32 v56, v88
	v_mov_b32_e32 v57, v89
	s_andn2_b64 exec, exec, s[8:9]
	s_cbranch_execnz .LBB0_1770
